# baseline (speedup 1.0000x reference)
;   __device__ __forceinline__ float* out() const { return reinterpret_cast<float*>(ld64(26 * 8)); }
;   __device__ __forceinline__ unsigned char* ws() const { return reinterpret_cast<unsigned char*>(ld64(27 * 8)); }
; __device__ __forceinline__ int opaque_tid() { int t = threadIdx.x; asm volatile("" : "+v"(t)); return t; }
; __device__ __forceinline__ void attn_sample_qkv(const PRef& p) {
;   const int tidx = opaque_tid();
;   const float* part = reinterpret_cast<const float*>(p.ws() + WS_PART);
;   bf16* Qb = (bf16*)(p.ws() + WS_Q); bf16* ksb = (bf16*)(p.ws() + WS_KS); bf16* vtb = (bf16*)(p.ws() + WS_VTS);
;   float* outs = p.out() + O_KVS;
;   for (int ms = blockIdx.x; ms < MS; ms += gridDim.x) {
;     const int b = ms >> 5, pos = PAST + (ms & 31);
; #pragma unroll
;     for (int i = 0; i < 3; ++i) {
;       const int c = i * 1024 + tidx * 2, region = c >> 9, cc = c & 511, half = (region >= 3) ? 512 : 0;
;       float2 v = *reinterpret_cast<const float2*>(part + (size_t)ms * 3072 + c);
; #pragma unroll
;       for (int k = 1; k < SPLIT_QKV; ++k) { const float2 t = *reinterpret_cast<const float2*>(part + (size_t)k * MS * 3072 + (size_t)ms * 3072 + c); v.x += t.x; v.y += t.y; }
;       if (region == 0 || region == 3) {
;         *reinterpret_cast<unsigned*>(Qb + (size_t)(MP + ms) * DM + half + cc) = cvtpk(v.x * QSCALE, v.y * QSCALE);
;       } else {
;         const int kvi = (region == 1) ? 0 : (region == 2) ? 1 : (region == 4) ? 2 : 3;
;         __builtin_nontemporal_store(f32x2{v.x, v.y}, reinterpret_cast<f32x2*>(outs + (size_t)kvi * MS * 512 + (size_t)ms * 512 + cc));
.LBB0_50:
	s_and_b64 vcc, exec, s[0:1]
	v_readlane_b32 s22, v254, 52
	s_cbranch_vccz .LBB0_283
	v_readlane_b32 s0, v254, 10
	s_cmp_lt_i32 s0, 6
	s_mov_b64 s[8:9], -1
	v_readlane_b32 s1, v254, 11
	s_cbranch_scc0 .LBB0_283
	v_mov_b32_e32 v2, 0x23fd8
	ds_read_b64 v[2:3], v2
	s_waitcnt lgkmcnt(0)
	v_readfirstlane_b32 s100, v2
	v_readfirstlane_b32 s101, v3
	v_readlane_b32 s0, v254, 5
	s_cmp_lg_u32 s0, -1
	s_mov_b64 s[6:7], src_shared_base
	s_cselect_b32 s0, s0, 0
	s_cselect_b32 s1, s7, 0
	v_mov_b64_e32 v[2:3], s[0:1]
	v_readlane_b32 s0, v254, 6
	s_cmp_lg_u32 s0, -1
	s_cselect_b32 s0, s0, 0
	s_cselect_b32 s1, s7, 0
	v_mov_b32_e32 v8, v171
	v_mov_b64_e32 v[4:5], s[0:1]
	flat_load_dword v0, v[2:3] sc0 sc1
	s_waitcnt vmcnt(0)
	flat_load_dword v6, v[4:5] sc0 sc1
	s_waitcnt vmcnt(0)
	s_add_i32 s6, 0, 0x23fd0
	s_cmp_lg_u32 s6, -1
	s_cselect_b32 s6, s6, 0
	s_cselect_b32 s8, s7, 0
	v_readlane_b32 s14, v254, 22
	v_readlane_b32 s15, v254, 23
	s_waitcnt lgkmcnt(0)
	v_readfirstlane_b32 s10, v0
	v_readfirstlane_b32 s11, v6
	flat_load_dword v0, v[2:3] sc0 sc1
	s_waitcnt vmcnt(0)
	flat_load_dword v6, v[4:5] sc0 sc1
	s_waitcnt vmcnt(0) lgkmcnt(0)
	v_readfirstlane_b32 s0, v0
	v_readfirstlane_b32 s1, v6
	flat_load_dword v0, v[2:3] sc0 sc1
	s_waitcnt vmcnt(0)
	flat_load_dword v6, v[4:5] sc0 sc1
	s_waitcnt vmcnt(0) lgkmcnt(0)
	v_readfirstlane_b32 s4, v0
	flat_load_dword v0, v[2:3] sc0 sc1
	s_waitcnt vmcnt(0)
	flat_load_dword v2, v[4:5] sc0 sc1
	s_waitcnt vmcnt(0)
	v_mov_b32_e32 v3, s8
	v_readfirstlane_b32 s5, v6
	s_waitcnt lgkmcnt(0)
	v_readfirstlane_b32 s12, v0
	v_readfirstlane_b32 s13, v2
	v_mov_b32_e32 v2, s6
	s_add_i32 s6, 0, 0x23fd4
	s_cmp_lg_u32 s6, -1
	s_cselect_b32 s6, s6, 0
	s_cselect_b32 s7, s7, 0
	flat_load_dword v0, v[2:3] sc0 sc1
	s_waitcnt vmcnt(0)
	v_mov_b32_e32 v2, s6
	v_mov_b32_e32 v3, s7
	flat_load_dword v2, v[2:3] sc0 sc1
	s_waitcnt vmcnt(0)
	s_andn2_b64 vcc, exec, s[14:15]
	s_waitcnt lgkmcnt(0)
	v_readfirstlane_b32 s8, v0
	v_cndmask_b32_e64 v0, 0, 1, s[14:15]
	v_cmp_ne_u32_e64 s[6:7], 1, v0
	v_readfirstlane_b32 s9, v2
	s_cbranch_vccnz .LBB0_115
	v_lshlrev_b32_e32 v22, 1, v8
	v_and_b32_e32 v9, 0x1fe, v22
	v_lshlrev_b32_e32 v0, 2, v9
	v_ashrrev_i32_e32 v11, 8, v8
	v_mov_b32_e32 v20, s10
	v_lshl_add_u64 v[2:3], s[8:9], 0, v[0:1]
	s_mov_b64 s[8:9], 0xc100000
	v_lshlrev_b32_e32 v0, 1, v9
	v_cmp_lt_i32_e32 vcc, 2, v11
	s_movk_i32 s10, 0x1ff
	s_add_u32 s24, s12, 0x6b00000
	v_lshl_add_u64 v[2:3], v[2:3], 0, s[8:9]
	v_lshl_add_u64 v[4:5], s[4:5], 0, v[0:1]
	v_lshl_add_u64 v[6:7], s[0:1], 0, v[0:1]
	s_mov_b64 s[0:1], 0x8c00000
	v_cndmask_b32_e32 v8, 0, v194, vcc
	v_cmp_lt_u32_e32 vcc, s10, v22
	v_cmp_ne_u32_e64 s[8:9], 3, v11
	v_add_u32_e32 v0, 0x400, v22
	s_addc_u32 s25, s13, 0
	v_lshl_add_u64 v[6:7], v[6:7], 0, s[0:1]
	s_and_b64 s[0:1], vcc, s[8:9]
	v_cmp_eq_u32_e32 vcc, 4, v11
	v_mov_b32_e32 v17, 0x60000
	v_mov_b32_e32 v18, 0x40000
	v_ashrrev_i32_e32 v13, 9, v0
	v_cndmask_b32_e32 v10, v17, v18, vcc
	v_cmp_lt_i32_e32 vcc, 2, v13
	s_mov_b64 s[4:5], 0xcd00000
	v_cmp_ne_u32_e64 s[8:9], 3, v13
	v_cndmask_b32_e32 v12, 0, v194, vcc
	v_cmp_lt_u32_e32 vcc, s10, v0
	v_add_u32_e32 v0, 0x800, v22
	v_lshl_add_u64 v[4:5], v[4:5], 0, s[4:5]
	s_and_b64 s[4:5], vcc, s[8:9]
	v_cmp_eq_u32_e32 vcc, 4, v13
	v_ashrrev_i32_e32 v15, 9, v0
	v_mov_b32_e32 v21, s11
	v_cndmask_b32_e32 v14, v17, v18, vcc
	v_cmp_lt_i32_e32 vcc, 2, v15
	v_ashrrev_i32_e32 v23, 31, v22
	v_cmp_ne_u32_e64 s[8:9], 3, v15
	v_cndmask_b32_e32 v16, 0, v194, vcc
	v_cmp_lt_u32_e32 vcc, s10, v0
	s_and_b64 s[10:11], vcc, s[8:9]
	v_lshl_add_u64 v[20:21], v[22:23], 2, v[20:21]
	s_mov_b64 s[8:9], 0xee00000
	v_cmp_eq_u32_e32 vcc, 4, v15
	v_lshl_add_u64 v[20:21], v[20:21], 0, s[8:9]
	v_readlane_b32 s8, v254, 0
	v_cndmask_b32_e32 v18, v17, v18, vcc
	s_mov_b32 s12, s8
	s_branch .LBB0_55

; __device__ __forceinline__ void attn_diff(const bf16* __restrict__ Qg, const bf16* __restrict__ Kg, const bf16* __restrict__ Vg, int vts, ...
;     ...
;     __syncthreads();
;     {
;       int mx = dn[0];
; #pragma unroll
;       for (int i = 1; i < 8; ++i) mx = max(mx, dn[i]);
;       if (mx <= it) break;
;     }
.LBB0_214:
	s_or_b64 exec, exec, s[0:1]
	v_mov_b32_e32 v80, 0x22040
	s_waitcnt lgkmcnt(0)
	s_barrier
	ds_read_b128 v[84:87], v80 offset:16
	ds_read_b128 v[80:83], v80
	v_add_u32_e32 v239, 0x80, v239
	v_add_u32_e32 v240, 0x80, v240
	v_add_u32_e32 v241, 0xffffff80, v241
	s_andn2_b64 s[0:1], s[94:95], exec
	s_waitcnt lgkmcnt(0)
	v_max3_i32 v0, v80, v81, v82
	v_max3_i32 v3, v83, v84, v85
	v_max3_i32 v0, v0, v86, v87
	v_max_i32_e32 v0, v0, v3
	v_cmp_ge_i32_e32 vcc, s86, v0
	s_and_b64 s[10:11], vcc, exec
	s_or_b64 s[94:95], s[0:1], s[10:11]

; __device__ __forceinline__ void dtile_load(u32x4 (&kr)[2], u32x4 (&vr)[2], const bf16* __restrict__ Kg, const bf16* __restrict__ Vg, int vts, int kt  , int part, int tidx) {
; #pragma unroll
;   for (int i = 0; i < 2; ++i) {
;     const int c = tidx + (2 * part + i) * NTHR;
;     kr[i] = *reinterpret_cast<const u32x4*>(Kg + (size_t)(kt * 128 + (c >> 4)) * 1024 + (c & 15) * 8);
;     vr[i] = *reinterpret_cast<const u32x4*>(Vg + (size_t)(c >> 4) * vts + kt * 128 + (c & 15) * 8);
;   }
; __device__ __forceinline__ void attn_diff(const bf16* __restrict__ Qg, const bf16* __restrict__ Kg, const bf16* __restrict__ Vg, int vts, ...
;     ...
;   for (int it = 0; it < nit; ++it) {
;     const int kt2 = kt_hi - 1 - it;
;     const char* bufc = lds + (it & 1) * ATT_BUF;
;     char* bufn = lds + ((it + 1) & 1) * ATT_BUF;
;     const bool more = it + 1 < nit;
;     if (more) dtile_load(kr, vr, Kg, Vg, vts, kt2 - 1, 0, tidx);
.LBB0_216:
	v_cmp_ne_u32_e32 vcc, s86, v236
	s_or_b64 s[94:95], s[94:95], exec
	s_and_saveexec_b64 s[82:83], vcc
	s_cbranch_execz .LBB0_215
	v_subrev_u32_e32 v5, s86, v226
	s_add_i32 s97, s86, 1
	v_cmp_lt_i32_e64 s[10:11], s97, v232
	v_lshlrev_b32_e32 v3, 7, v5
	s_cmp_lg_u32 s86, 0
	s_cbranch_scc1 .Lmy_offs_ready
	v_add_u32_e32 v80, 0xffffff80, v3
	v_subrev_u32_e32 v81, s100, v158
	v_add_u32_e32 v82, v80, v227
	v_lshl_add_u32 v6, v82, 11, v81
	v_add_u32_e32 v82, v80, v228
	v_lshl_add_u32 v8, v82, 11, v81
	v_add_u32_e32 v82, v80, v229
	v_lshl_add_u32 v10, v82, 11, v81
	v_add_u32_e32 v82, v80, v230
	v_lshl_add_u32 v12, v82, 11, v81
	v_subrev_u32_e32 v81, s100, v172
	v_lshl_add_u32 v81, v80, 1, v81
	v_lshl_add_u32 v7, v160, 1, v81
	v_lshl_add_u32 v9, v162, 1, v81
	v_lshl_add_u32 v11, v164, 1, v81
	v_lshl_add_u32 v13, v166, 1, v81
.Lmy_offs_ready:
	s_and_saveexec_b64 s[0:1], s[10:11]
	s_cbranch_execz .LBB0_221
	global_load_dwordx4 v[128:131], v6, s[100:101]
	global_load_dwordx4 v[132:135], v7, s[100:101]
	global_load_dwordx4 v[140:143], v9, s[100:101]
	global_load_dwordx4 v[136:139], v8, s[100:101]
	v_add_u32_e32 v6, 0xfffc0000, v6
	v_add_u32_e32 v7, 0xffffff00, v7
	v_add_u32_e32 v9, 0xffffff00, v9
	v_add_u32_e32 v8, 0xfffc0000, v8
.LBB0_221:
	s_or_b64 exec, exec, s[0:1]
	s_xor_b64 s[0:1], s[8:9], -1
	s_bitcmp1_b32 s86, 0
	s_cselect_b32 s12, 0x11000, 0
	s_bitcmp1_b32 s97, 0
	s_cselect_b32 s13, 0x11000, 0
	s_mov_b32 s84, 0
	v_add_u32_e32 v4, s13, v170
	v_lshrrev_b32_e32 v80, 4, v150
	v_add_u32_e32 v14, s12, v237
	v_add_u32_e32 v15, s12, v238
	v_mad_u32_u24 v4, v80, s33, v4
	v_mov_b32_e32 v144, v241
	v_mov_b32_e32 v242, v240
	v_mov_b32_e32 v243, v239
	s_branch .LBB0_223

; __device__ __forceinline__ void dtile_store(const u32x4 (&kr)[2], const u32x4 (&vr)[2], char* buf, int part, int tidx) {
; #pragma unroll
;   for (int i = 0; i < 2; ++i) {
;     const int c = tidx + (2 * part + i) * NTHR;
;     *reinterpret_cast<u32x4*>(buf + (c >> 4) * KSTR_D + (c & 15) * 16) = kr[i];
;     *reinterpret_cast<u32x4*>(buf + VOFF_D + (c >> 4) * VSTR_D + (c & 15) * 16) = vr[i];
;   }
; }
; __device__ __forceinline__ void attn_diff(const bf16* __restrict__ Qg, const bf16* __restrict__ Kg, const bf16* __restrict__ Vg, int vts, ...
;     ...
;       if (more) { dtile_store(kr, vr, bufn, 1 - hf, tidx); if (hf == 1) dtile_load(kr, vr, Kg, Vg, vts, kt2 - 1, 1, tidx); }
;     }
;     if (!done_w && kt2 > 0 && kt2 * 128 < kmax_w) {
;       const float kbn = sqrtf(pm[g * 128 + kt2 * 2]) * 1.001f;
;       const float lhs = fmaf(qn, kbn, nslope * (float)(qpos_w + j - (kt2 * 128 - 1))) - mref + __builtin_amdgcn_logf((float)(kt2 * 128));
;       if (__all(lhs <= __builtin_amdgcn_logf(l) - 30.f)) { done_w = true; if (lane == 0) dn[w] = it; }
.LBB0_231:
	s_or_b64 exec, exec, s[90:91]
	s_and_saveexec_b64 s[12:13], s[10:11]
	s_cbranch_execz .LBB0_222
	s_waitcnt vmcnt(0) lgkmcnt(0)
	s_cmp_lg_u32 s84, 0
	s_cbranch_scc1 .Lmy_st1
	ds_write_b128 v4, v[128:131]
	ds_write_b128 v4, v[132:135] offset:34816
	ds_write_b128 v4, v[136:139] offset:8704
	ds_write_b128 v4, v[140:143] offset:43520
	global_load_dwordx4 v[128:131], v10, s[100:101]
	global_load_dwordx4 v[132:135], v11, s[100:101]
	global_load_dwordx4 v[136:139], v12, s[100:101]
	global_load_dwordx4 v[140:143], v13, s[100:101]
	v_add_u32_e32 v10, 0xfffc0000, v10
	v_add_u32_e32 v11, 0xffffff00, v11
	v_add_u32_e32 v12, 0xfffc0000, v12
	v_add_u32_e32 v13, 0xffffff00, v13
	s_branch .LBB0_222
.Lmy_st1:
	ds_write_b128 v4, v[128:131] offset:17408
	ds_write_b128 v4, v[132:135] offset:52224
	ds_write_b128 v4, v[136:139] offset:26112
	ds_write_b128 v4, v[140:143] offset:60928
	s_branch .LBB0_222
.LBB0_234:
	v_cmp_lt_i32_e32 vcc, 0, v5
	s_and_b64 s[10:11], s[0:1], vcc
	s_and_saveexec_b64 s[0:1], s[10:11]
	s_cbranch_execz .LBB0_214
	v_cmp_lt_i32_e32 vcc, v3, v231
	s_mov_b64 s[10:11], 0
	s_and_saveexec_b64 s[12:13], vcc
	s_cbranch_execz .LBB0_213
	s_mov_b64 s[10:11], src_shared_base
	v_lshl_add_u32 v4, v5, 3, v234
	v_mov_b32_e32 v5, s11
	flat_load_dword v0, v[4:5] sc0 sc1
	s_waitcnt vmcnt(0)
	s_mov_b32 s10, 0xf800000
	s_waitcnt lgkmcnt(0)
	v_cmp_gt_f32_e32 vcc, s10, v0
	v_mul_f32_e32 v4, 0x4f800000, v0
	s_nop 0
	v_cndmask_b32_e32 v0, v0, v4, vcc
	v_sqrt_f32_e32 v4, v0
	s_nop 0
	v_add_u32_e32 v5, -1, v4
	v_fma_f32 v80, -v5, v4, v0
	v_cmp_ge_f32_e64 s[10:11], 0, v80
	v_add_u32_e32 v80, 1, v4
	s_nop 0
	v_cndmask_b32_e64 v5, v4, v5, s[10:11]
	v_fma_f32 v4, -v80, v4, v0
	v_cmp_lt_f32_e64 s[10:11], 0, v4
	s_nop 1
	v_cndmask_b32_e64 v4, v5, v80, s[10:11]
	v_mul_f32_e32 v5, 0x37800000, v4
	v_cndmask_b32_e32 v4, v4, v5, vcc
	v_cmp_class_f32_e32 vcc, v0, v192
	v_log_f32_e32 v5, v224
	s_nop 0
	v_cndmask_b32_e32 v0, v4, v0, vcc
	v_sub_u32_e32 v4, v235, v3
	v_cvt_f32_i32_e32 v4, v4
	v_mul_f32_e32 v0, 0x3f8020c5, v0
	v_mul_f32_e32 v4, v168, v4
	v_fmac_f32_e32 v4, v225, v0
	v_cvt_f32_u32_e32 v0, v3
	v_sub_f32_e32 v144, v4, v2
	v_log_f32_e32 v4, v0
	s_nop 0
	v_pk_add_f32 v[4:5], v[4:5], v[144:145]
	s_nop 0
	v_cmp_le_f32_e32 vcc, v4, v5
	s_cmp_eq_u64 vcc, exec
	s_cselect_b64 s[10:11], -1, 0
	s_and_b64 s[16:17], s[4:5], s[10:11]
	s_and_saveexec_b64 s[14:15], s[16:17]
	s_cbranch_execz .LBB0_212
	v_mov_b32_e32 v0, s86
	s_or_b64 s[10:11], s[10:11], exec
	flat_store_dword v[174:175], v0 sc0 sc1
	s_waitcnt vmcnt(0)
	s_branch .LBB0_212

; template <unsigned MASK>
; __global__ void __launch_bounds__(NTHR) mega(Params pk) {
;   extern __shared__ __attribute__((aligned(16))) char smem[];
	.amdhsa_kernel _Z4megaILj2047EEv6Params
		.amdhsa_group_segment_fixed_size 0
		.amdhsa_private_segment_fixed_size 0
		.amdhsa_kernarg_size 488
		.amdhsa_user_sgpr_count 2
		.amdhsa_user_sgpr_dispatch_ptr 0
		.amdhsa_user_sgpr_queue_ptr 0
		.amdhsa_user_sgpr_kernarg_segment_ptr 1
		.amdhsa_user_sgpr_dispatch_id 0
		.amdhsa_user_sgpr_kernarg_preload_length 0
		.amdhsa_user_sgpr_kernarg_preload_offset 0
		.amdhsa_user_sgpr_private_segment_size 0
		.amdhsa_uses_dynamic_stack 0
		.amdhsa_enable_private_segment 0
		.amdhsa_system_sgpr_workgroup_id_x 1
		.amdhsa_system_sgpr_workgroup_id_y 0
		.amdhsa_system_sgpr_workgroup_id_z 0
		.amdhsa_system_sgpr_workgroup_info 0
		.amdhsa_system_vgpr_workitem_id 2
		.amdhsa_next_free_vgpr 256
		.amdhsa_next_free_sgpr 102
		.amdhsa_accum_offset 256
		.amdhsa_reserve_vcc 1
		.amdhsa_float_round_mode_32 0
		.amdhsa_float_round_mode_16_64 0
		.amdhsa_float_denorm_mode_32 3
		.amdhsa_float_denorm_mode_16_64 3
		.amdhsa_dx10_clamp 1
		.amdhsa_ieee_mode 1
		.amdhsa_fp16_overflow 0
		.amdhsa_tg_split 0
		.amdhsa_exception_fp_ieee_invalid_op 0
		.amdhsa_exception_fp_denorm_src 0
		.amdhsa_exception_fp_ieee_div_zero 0
		.amdhsa_exception_fp_ieee_overflow 0
		.amdhsa_exception_fp_ieee_underflow 0
		.amdhsa_exception_fp_ieee_inexact 0
		.amdhsa_exception_int_div_zero 0
	.end_amdhsa_kernel

; template <unsigned MASK>
; __global__ void __launch_bounds__(NTHR) mega(Params pk) {
amdhsa.kernels:
  - .agpr_count:     0
    .args:
      - .offset:         0
        .size:           232
        .value_kind:     by_value
      - .offset:         232
        .size:           4
        .value_kind:     hidden_block_count_x
      - .offset:         236
        .size:           4
        .value_kind:     hidden_block_count_y
      - .offset:         240
        .size:           4
        .value_kind:     hidden_block_count_z
      - .offset:         244
        .size:           2
        .value_kind:     hidden_group_size_x
      - .offset:         246
        .size:           2
        .value_kind:     hidden_group_size_y
      - .offset:         248
        .size:           2
        .value_kind:     hidden_group_size_z
      - .offset:         250
        .size:           2
        .value_kind:     hidden_remainder_x
      - .offset:         252
        .size:           2
        .value_kind:     hidden_remainder_y
      - .offset:         254
        .size:           2
        .value_kind:     hidden_remainder_z
      - .offset:         272
        .size:           8
        .value_kind:     hidden_global_offset_x
      - .offset:         280
        .size:           8
        .value_kind:     hidden_global_offset_y
      - .offset:         288
        .size:           8
        .value_kind:     hidden_global_offset_z
      - .offset:         296
        .size:           2
        .value_kind:     hidden_grid_dims
      - .offset:         320
        .size:           8
        .value_kind:     hidden_multigrid_sync_arg
      - .offset:         352
        .size:           4
        .value_kind:     hidden_dynamic_lds_size
    .group_segment_fixed_size: 0
    .kernarg_segment_align: 8
    .kernarg_segment_size: 488
    .language:       OpenCL C
    .language_version:
      - 2
      - 0
    .max_flat_workgroup_size: 512
    .name:           _Z4megaILj2047EEv6Params
    .private_segment_fixed_size: 0
    .sgpr_count:     108
    .sgpr_spill_count: 85
    .symbol:         _Z4megaILj2047EEv6Params.kd
    .uniform_work_group_size: 1
    .uses_dynamic_stack: false
    .vgpr_count:     256
    .vgpr_spill_count: 0
    .wavefront_size: 64
